# v130 variant: GDN snapshot record layout [w][half][lane] instead of the permlane32 store exchange, plus newest-first GDN head-output item order in phase 3b
# baseline (speedup 1.0000x reference)
.LBB0_1031:
	v_cmp_lt_i32_e32 vcc, v21, v22
	v_mov_b32_e32 v0, v181
	s_ashr_i32 s0, s39, 3
	v_cndmask_b32_e32 v2, v20, v21, vcc
	v_cmp_lt_i32_e32 vcc, v23, v22
	s_waitcnt vmcnt(28)
	v_lshlrev_b32_e32 v33, 2, v2
	v_ashrrev_i32_e32 v2, 6, v0
	v_cndmask_b32_e32 v3, v20, v23, vcc
	v_cmp_lt_i32_e32 vcc, v24, v22
	v_lshlrev_b32_e32 v32, 2, v3
	v_and_b32_e32 v3, 63, v0
	v_cndmask_b32_e32 v4, v20, v24, vcc
	v_cmp_lt_i32_e32 vcc, v25, v22
	v_lshlrev_b32_e32 v31, 2, v4
	v_and_b32_e32 v4, 15, v0
	v_cndmask_b32_e32 v5, v20, v25, vcc
	v_lshlrev_b32_e32 v30, 2, v5
	v_lshrrev_b32_e32 v0, 2, v0
	v_lshlrev_b32_e32 v5, 4, v2
	s_lshl_b32 s1, s39, 7
	v_and_b32_e32 v6, 12, v0
	v_lshlrev_b32_e32 v7, 2, v3
	v_lshlrev_b32_e32 v12, 4, v3
	v_lshl_add_u32 v3, s0, 6, v5
	s_and_b32 s4, s39, 0xfffffc00
	s_and_b32 s8, s1, 0x380
	v_lshlrev_b32_e32 v8, 1, v4
	v_lshlrev_b32_e32 v0, 2, v4
	v_or_b32_e32 v5, v5, v4
	v_or_b32_e32 v4, v3, v6
	s_and_b32 s1, s0, 0x7f
	s_or_b32 s4, s8, s4
	global_load_dword v29, v0, s[40:41]
	global_load_dword v28, v0, s[40:41] offset:64
	global_load_dword v27, v0, s[40:41] offset:128
	global_load_dword v26, v0, s[40:41] offset:192
	v_lshlrev_b32_e32 v0, 1, v6
	v_lshlrev_b32_e32 v6, 6, v5
	v_ashrrev_i32_e32 v5, 31, v4
	s_or_b32 s4, s4, s1
	s_waitcnt vmcnt(28)
	v_lshlrev_b64 v[66:67], 13, v[4:5]
	s_ashr_i32 s5, s4, 31
	v_or_b32_e32 v14, 1, v4
	v_or_b32_e32 v16, 2, v4
	v_or_b32_e32 v18, 3, v4
	v_lshl_add_u64 v[4:5], s[20:21], 0, v[66:67]
	s_lshl_b64 s[0:1], s[4:5], 13
	v_lshl_add_u64 v[4:5], v[4:5], 0, s[8:9]
	s_add_u32 s4, s50, s0
	v_lshl_add_u64 v[50:51], v[4:5], 0, v[8:9]
	s_addc_u32 s5, s51, s1
	v_add_co_u32_e32 v52, vcc, s36, v50
	s_add_u32 s6, s17, s0
	s_nop 0
	v_addc_co_u32_e32 v53, vcc, 0, v51, vcc
	v_lshl_or_b32 v2, v2, 10, v7
	v_ashrrev_i32_e32 v7, 31, v6
	s_addc_u32 s7, s29, s1
	v_add_co_u32_e32 v54, vcc, s37, v50
	v_mov_b32_e32 v1, v9
	v_ashrrev_i32_e32 v3, 31, v2
	v_lshl_add_u64 v[6:7], v[6:7], 1, s[4:5]
	s_add_u32 s0, s15, s0
	v_addc_co_u32_e32 v55, vcc, 0, v51, vcc
	v_mov_b32_e32 v13, v9
	v_lshl_add_u64 v[34:35], v[6:7], 0, v[0:1]
	v_lshl_add_u64 v[36:37], v[2:3], 1, s[6:7]
	s_addc_u32 s1, s16, s1
	v_add_co_u32_e32 v56, vcc, s38, v50
	global_load_dwordx2 v[4:5], v[34:35], off
	global_load_dwordx2 v[6:7], v[34:35], off offset:32
	global_load_dwordx2 v[0:1], v[34:35], off offset:64
	global_load_dwordx2 v[2:3], v[34:35], off offset:96
	global_load_dwordx2 v[68:69], v[36:37], off
	global_load_dwordx2 v[72:73], v[36:37], off offset:512
	global_load_dwordx2 v[76:77], v[36:37], off offset:1024
	global_load_dwordx2 v[80:81], v[36:37], off offset:1536
	v_addc_co_u32_e32 v57, vcc, 0, v51, vcc
	global_load_ushort v82, v[50:51], off offset:3072
	global_load_ushort v83, v[50:51], off offset:3104
	global_load_ushort v84, v[50:51], off offset:3136
	global_load_ushort v85, v[50:51], off offset:3168
	global_load_dwordx4 v[34:37], v12, s[0:1]
	global_load_dwordx4 v[38:41], v12, s[0:1] offset:2048
	global_load_dwordx4 v[42:45], v12, s[0:1] offset:1024
	global_load_dwordx4 v[46:49], v12, s[0:1] offset:3072
	global_load_ushort v86, v[52:53], off offset:3072
	global_load_ushort v87, v[54:55], off offset:3072
	global_load_ushort v88, v[56:57], off offset:3072
	global_load_ushort v89, v[52:53], off offset:3104
	global_load_ushort v90, v[54:55], off offset:3104
	global_load_ushort v91, v[56:57], off offset:3104
	global_load_ushort v92, v[52:53], off offset:3136
	global_load_ushort v93, v[54:55], off offset:3136
	global_load_ushort v94, v[56:57], off offset:3136
	global_load_ushort v95, v[54:55], off offset:3168
	global_load_ushort v96, v[52:53], off offset:3168
	global_load_ushort v97, v[56:57], off offset:3168
	v_lshl_add_u64 v[12:13], s[0:1], 0, v[12:13]
	v_lshl_add_u64 v[70:71], v[12:13], 0, s[10:11]
	s_waitcnt vmcnt(55)
	v_lshl_add_u64 v[74:75], v[12:13], 0, s[12:13]
	v_add_co_u32_e32 v12, vcc, s34, v12
	s_add_u32 s0, s20, s8
	s_nop 0
	v_addc_co_u32_e32 v13, vcc, 0, v13, vcc
	global_load_dwordx4 v[50:53], v[12:13], off
	global_load_dwordx4 v[54:57], v[12:13], off offset:2048
	global_load_dwordx4 v[58:61], v[70:71], off offset:1024
	global_load_dwordx4 v[62:65], v[74:75], off offset:1024
	s_addc_u32 s1, s21, 0
	v_and_b32_e32 v12, 0xffe00000, v66
	v_lshrrev_b32_e32 v13, 5, v66
	v_and_b32_e32 v13, 0xe000, v13
	v_lshrrev_b32_e32 v14, 7, v66
	v_and_b32_e32 v14, 0x7c0, v14
	v_lshrrev_b32_e32 v15, 10, v66
	v_and_b32_e32 v15, 32, v15
	v_and_b32_e32 v16, 30, v8
	v_or3_b32 v12, v12, v13, v14
	v_or3_b32 v12, v12, v15, v16
	s_lshl_b32 s8, s8, 10
	v_add_u32_e32 v12, s8, v12
	v_xor_b32_e32 v16, 16, v12
	v_add_u32_e32 v14, 64, v12
	v_add_u32_e32 v18, 0xc0, v16
	v_add_u32_e32 v16, 0x80, v16
	v_xor_b32_e32 v13, 32, v12
	v_xor_b32_e32 v15, 32, v14
	v_xor_b32_e32 v17, 32, v16
	v_xor_b32_e32 v19, 32, v18
	s_add_i32 s8, s39, 0x400
	s_cmpk_lt_i32 s8, 0x1000
	s_cbranch_scc1 .Lp3b_nx
	s_and_b32 s8, s39, 0x1ff
	s_bitcmp1_b32 s39, 9
